# p7 second-half epilogue: issue all 16 gate loads up front (on top of p10+p12 epilogue edits)
# baseline (speedup 1.0000x reference)
; __device__ __forceinline__ void unpack8(const u32x4 r, float (&o)[8]) { o[0] = bflo(r.x); o[1] = bfhi(r.x); o[2] = bflo(r.y); o[3] = bfhi(r.y); o[4] = bflo(r.z); o[5] = bfhi(r.z); o[6] = bflo(r.w); o[7] = bfhi(r.w); }
; __device__ __forceinline__ u32x4 pack8(const float (&o)[8]) { u32x4 r; r.x = pk2(o[0], o[1]); r.y = pk2(o[2], o[3]); r.z = pk2(o[4], o[5]); r.w = pk2(o[6], o[7]); return r; }
; __device__ __forceinline__ float sigmoidf_(float x) { return __builtin_amdgcn_rcpf(1.0f + __expf(-x)); }
;     __device__ __forceinline__ bool operator()(f32x4 (&acc)[2][2][4][2], const Unit& u, int wr, int wc, int fr, int fq) const {
;     ...
; #pragma unroll
;         for (int ai = 0; ai < 2; ++ai)
; #pragma unroll
;             for (int m = 0; m < 4; ++m)
; #pragma unroll
;                 for (int bj = 0; bj < 2; ++bj) { const size_t off = (size_t)(row0 + ai * 128 + m * 16) * DM + u.pn * 256 + cl0 + bj * 128;
;                     float b[8], r[8]; unpack8(*(const u32x4*)(gp + off), b);
; #pragma unroll
;                     for (int e = 0; e < 4; ++e) { r[e] = acc[ai][bj][m][0][e] * sigmoidf_(b[e]); r[4 + e] = acc[ai][bj][m][1][e] * sigmoidf_(b[4 + e]); }
;                     *(u32x4*)(o + off) = pack8(r); }
;         return false;
.LBB0_614:
	s_cmp_lg_u32 s33, 0
	v_lshl_add_u32 v146, s2, 8, v155
	s_cselect_b64 s[44:45], -1, 0
	s_lshl_b32 s2, s3, 8
	s_ashr_i32 s3, s2, 31
	v_ashrrev_i32_e32 v147, 31, v146
	v_lshlrev_b64 v[134:135], 11, v[146:147]
	v_mov_b32_e32 v5, s3
	v_or_b32_e32 v4, s2, v164
	s_nop 15
	s_nop 7
	v_lshl_add_u64 v[134:135], v[134:135], 0, v[4:5]
	v_lshlrev_b64 v[142:143], 1, v[134:135]
	v_or_b32_e32 v150, 16, v146
	v_or_b32_e32 v174, 32, v146
	v_or_b32_e32 v172, 48, v146
	s_cmp_eq_u32 s33, 0
	v_lshl_add_u64 v[134:135], s[12:13], 0, v[142:143]
	v_or_b32_e32 v148, 0x100, v142
	v_ashrrev_i32_e32 v151, 31, v150
	v_ashrrev_i32_e32 v175, 31, v174
	v_ashrrev_i32_e32 v173, 31, v172
	v_readlane_b32 s70, v235, 53
	s_cbranch_scc1 .LBB0_622
	global_load_dwordx4 v[136:139], v[134:135], off
	global_load_dwordx4 v[184:187], v[134:135], off offset:256
	v_add_co_u32_e32 v224, vcc, 0x10000, v134
	s_nop 1
	v_addc_co_u32_e32 v225, vcc, 0, v135, vcc
	global_load_dwordx4 v[188:191], v[224:225], off
	global_load_dwordx4 v[192:195], v[224:225], off offset:256
	v_add_co_u32_e32 v224, vcc, 0x10000, v224
	s_nop 1
	v_addc_co_u32_e32 v225, vcc, 0, v225, vcc
	global_load_dwordx4 v[196:199], v[224:225], off
	global_load_dwordx4 v[200:203], v[224:225], off offset:256
	v_add_co_u32_e32 v224, vcc, 0x10000, v224
	s_nop 1
	v_addc_co_u32_e32 v225, vcc, 0, v225, vcc
	global_load_dwordx4 v[204:207], v[224:225], off
	global_load_dwordx4 v[208:211], v[224:225], off offset:256
	v_add_co_u32_e32 v224, vcc, 0x50000, v224
	s_nop 1
	v_addc_co_u32_e32 v225, vcc, 0, v225, vcc
	global_load_dwordx4 v[212:215], v[224:225], off
	global_load_dwordx4 v[216:219], v[224:225], off offset:256
	v_add_co_u32_e32 v224, vcc, 0x10000, v224
	s_nop 1
	v_addc_co_u32_e32 v225, vcc, 0, v225, vcc
	global_load_dwordx4 v[220:223], v[224:225], off
	global_load_dwordx4 v[226:229], v[224:225], off offset:256
	v_add_co_u32_e32 v224, vcc, 0x10000, v224
	s_nop 1
	v_addc_co_u32_e32 v225, vcc, 0, v225, vcc
	global_load_dwordx4 v[230:233], v[224:225], off
	global_load_dwordx4 v[236:239], v[224:225], off offset:256
	v_add_co_u32_e32 v224, vcc, 0x10000, v224
	s_nop 1
	v_addc_co_u32_e32 v225, vcc, 0, v225, vcc
	global_load_dwordx4 v[240:243], v[224:225], off
	global_load_dwordx4 v[244:247], v[224:225], off offset:256
	v_mov_b32_e32 v149, v143
	v_lshl_add_u64 v[140:141], s[12:13], 0, v[148:149]
	s_waitcnt vmcnt(0)
	v_lshlrev_b32_e32 v3, 16, v136
	v_and_b32_e32 v136, 0xffff0000, v136
	v_lshlrev_b32_e32 v144, 16, v137
	v_and_b32_e32 v137, 0xffff0000, v137
	v_lshlrev_b32_e32 v145, 16, v138
	v_and_b32_e32 v138, 0xffff0000, v138
	v_lshlrev_b32_e32 v152, 16, v139
	v_and_b32_e32 v139, 0xffff0000, v139
	v_mul_f32_e32 v136, 0xbfb8aa3b, v136
	v_mul_f32_e32 v138, 0xbfb8aa3b, v138
	v_mul_f32_e32 v137, 0xbfb8aa3b, v137
	v_mul_f32_e32 v139, 0xbfb8aa3b, v139
	v_mul_f32_e32 v3, 0xbfb8aa3b, v3
	v_mul_f32_e32 v145, 0xbfb8aa3b, v145
	v_mul_f32_e32 v144, 0xbfb8aa3b, v144
	v_mul_f32_e32 v152, 0xbfb8aa3b, v152
	v_exp_f32_e32 v136, v136
	v_exp_f32_e32 v138, v138
	v_exp_f32_e32 v137, v137
	v_exp_f32_e32 v139, v139
	v_exp_f32_e32 v3, v3
	v_exp_f32_e32 v145, v145
	v_exp_f32_e32 v144, v144
	v_exp_f32_e32 v152, v152
	v_add_f32_e32 v136, 1.0, v136
	v_add_f32_e32 v138, 1.0, v138
	v_add_f32_e32 v137, 1.0, v137
	v_add_f32_e32 v139, 1.0, v139
	v_add_f32_e32 v3, 1.0, v3
	v_add_f32_e32 v145, 1.0, v145
	v_add_f32_e32 v144, 1.0, v144
	v_add_f32_e32 v152, 1.0, v152
	v_rcp_f32_e32 v136, v136
	v_rcp_f32_e32 v138, v138
	v_rcp_f32_e32 v137, v137
	v_rcp_f32_e32 v139, v139
	v_rcp_f32_e32 v3, v3
	v_rcp_f32_e32 v145, v145
	v_rcp_f32_e32 v144, v144
	v_rcp_f32_e32 v152, v152
	v_mul_f32_e32 v136, v131, v136
	v_mul_f32_e32 v138, v127, v138
	v_mul_f32_e32 v137, v133, v137
	v_mul_f32_e32 v139, v129, v139
	v_mul_f32_e32 v3, v130, v3
	v_mul_f32_e32 v145, v126, v145
	v_mul_f32_e32 v144, v132, v144
	v_mul_f32_e32 v152, v128, v152
	v_cvt_pk_bf16_f32 v136, v3, v136
	v_cvt_pk_bf16_f32 v137, v144, v137
	v_cvt_pk_bf16_f32 v138, v145, v138
	v_cvt_pk_bf16_f32 v139, v152, v139
	s_nop 0
	v_lshl_add_u64 v[140:141], s[8:9], 0, v[142:143]
	global_store_dwordx4 v[140:141], v[136:139], off
	v_lshl_add_u64 v[152:153], s[8:9], 0, v[148:149]
	v_lshlrev_b64 v[144:145], 11, v[150:151]
	v_lshl_add_u64 v[144:145], v[144:145], 0, v[4:5]
	v_lshlrev_b64 v[144:145], 1, v[144:145]
	v_lshl_add_u64 v[180:181], s[12:13], 0, v[144:145]
	s_nop 0
	v_and_b32_e32 v136, 0xffff0000, v184
	v_lshlrev_b32_e32 v137, 16, v185
	v_and_b32_e32 v138, 0xffff0000, v185
	v_lshlrev_b32_e32 v139, 16, v186
	v_lshlrev_b32_e32 v3, 16, v184
	v_and_b32_e32 v140, 0xffff0000, v186
	v_lshlrev_b32_e32 v141, 16, v187
	v_and_b32_e32 v149, 0xffff0000, v187
	v_mul_f32_e32 v139, 0xbfb8aa3b, v139
	v_mul_f32_e32 v136, 0xbfb8aa3b, v136
	v_mul_f32_e32 v137, 0xbfb8aa3b, v137
	v_mul_f32_e32 v138, 0xbfb8aa3b, v138
	v_mul_f32_e32 v3, 0xbfb8aa3b, v3
	v_mul_f32_e32 v140, 0xbfb8aa3b, v140
	v_mul_f32_e32 v141, 0xbfb8aa3b, v141
	v_mul_f32_e32 v149, 0xbfb8aa3b, v149
	v_exp_f32_e32 v139, v139
	v_exp_f32_e32 v136, v136
	v_exp_f32_e32 v137, v137
	v_exp_f32_e32 v138, v138
	v_exp_f32_e32 v3, v3
	v_exp_f32_e32 v140, v140
	v_exp_f32_e32 v141, v141
	v_exp_f32_e32 v149, v149
	v_add_f32_e32 v139, 1.0, v139
	v_add_f32_e32 v136, 1.0, v136
	v_add_f32_e32 v137, 1.0, v137
	v_add_f32_e32 v138, 1.0, v138
	v_add_f32_e32 v3, 1.0, v3
	v_add_f32_e32 v140, 1.0, v140
	v_add_f32_e32 v141, 1.0, v141
	v_add_f32_e32 v149, 1.0, v149
	v_rcp_f32_e32 v139, v139
	v_rcp_f32_e32 v136, v136
	v_rcp_f32_e32 v137, v137
	v_rcp_f32_e32 v138, v138
	v_rcp_f32_e32 v3, v3
	v_rcp_f32_e32 v140, v140
	v_rcp_f32_e32 v141, v141
	v_rcp_f32_e32 v149, v149
	v_mul_f32_e32 v139, v94, v139
	v_mul_f32_e32 v136, v99, v136
; __device__ __forceinline__ void unpack8(const u32x4 r, float (&o)[8]) { o[0] = bflo(r.x); o[1] = bfhi(r.x); o[2] = bflo(r.y); o[3] = bfhi(r.y); o[4] = bflo(r.z); o[5] = bfhi(r.z); o[6] = bflo(r.w); o[7] = bfhi(r.w); }
; __device__ __forceinline__ u32x4 pack8(const float (&o)[8]) { u32x4 r; r.x = pk2(o[0], o[1]); r.y = pk2(o[2], o[3]); r.z = pk2(o[4], o[5]); r.w = pk2(o[6], o[7]); return r; }
; __device__ __forceinline__ float sigmoidf_(float x) { return __builtin_amdgcn_rcpf(1.0f + __expf(-x)); }
;     __device__ __forceinline__ bool operator()(f32x4 (&acc)[2][2][4][2], const Unit& u, int wr, int wc, int fr, int fq) const {
;     ...
;                 for (int bj = 0; bj < 2; ++bj) { const size_t off = (size_t)(row0 + ai * 128 + m * 16) * DM + u.pn * 256 + cl0 + bj * 128;
;                     float b[8], r[8]; unpack8(*(const u32x4*)(gp + off), b);
; #pragma unroll
;                     for (int e = 0; e < 4; ++e) { r[e] = acc[ai][bj][m][0][e] * sigmoidf_(b[e]); r[4 + e] = acc[ai][bj][m][1][e] * sigmoidf_(b[4 + e]); }
;                     *(u32x4*)(o + off) = pack8(r); }
	v_mul_f32_e32 v137, v100, v137
	v_mul_f32_e32 v138, v101, v138
	v_mul_f32_e32 v3, v98, v3
	v_mul_f32_e32 v140, v95, v140
	v_mul_f32_e32 v141, v96, v141
	v_mul_f32_e32 v149, v97, v149
	v_cvt_pk_bf16_f32 v136, v3, v136
	v_cvt_pk_bf16_f32 v137, v137, v138
	v_cvt_pk_bf16_f32 v138, v139, v140
	v_cvt_pk_bf16_f32 v139, v141, v149
	global_store_dwordx4 v[152:153], v[136:139], off
	s_nop 0
	v_lshl_add_u64 v[140:141], s[8:9], 0, v[144:145]
	v_or_b32_e32 v144, 0x100, v144
	v_lshl_add_u64 v[152:153], s[12:13], 0, v[144:145]
	v_lshl_add_u64 v[144:145], s[8:9], 0, v[144:145]
	s_nop 0
	v_lshlrev_b32_e32 v3, 16, v188
	v_and_b32_e32 v136, 0xffff0000, v188
	v_lshlrev_b32_e32 v149, 16, v189
	v_and_b32_e32 v137, 0xffff0000, v189
	v_lshlrev_b32_e32 v176, 16, v190
	v_and_b32_e32 v138, 0xffff0000, v190
	v_lshlrev_b32_e32 v177, 16, v191
	v_and_b32_e32 v139, 0xffff0000, v191
	v_mul_f32_e32 v176, 0xbfb8aa3b, v176
	v_mul_f32_e32 v136, 0xbfb8aa3b, v136
	v_mul_f32_e32 v138, 0xbfb8aa3b, v138
	v_mul_f32_e32 v177, 0xbfb8aa3b, v177
	v_mul_f32_e32 v137, 0xbfb8aa3b, v137
	v_mul_f32_e32 v139, 0xbfb8aa3b, v139
	v_mul_f32_e32 v3, 0xbfb8aa3b, v3
	v_mul_f32_e32 v149, 0xbfb8aa3b, v149
	v_exp_f32_e32 v176, v176
	v_exp_f32_e32 v136, v136
	v_exp_f32_e32 v138, v138
	v_exp_f32_e32 v177, v177
	v_exp_f32_e32 v137, v137
	v_exp_f32_e32 v139, v139
	v_exp_f32_e32 v3, v3
	v_exp_f32_e32 v149, v149
	v_add_f32_e32 v176, 1.0, v176
	v_add_f32_e32 v136, 1.0, v136
	v_add_f32_e32 v138, 1.0, v138
	v_add_f32_e32 v177, 1.0, v177
	v_add_f32_e32 v137, 1.0, v137
	v_add_f32_e32 v139, 1.0, v139
	v_add_f32_e32 v3, 1.0, v3
	v_add_f32_e32 v149, 1.0, v149
	v_rcp_f32_e32 v176, v176
	v_rcp_f32_e32 v136, v136
	v_rcp_f32_e32 v138, v138
	v_rcp_f32_e32 v177, v177
	v_rcp_f32_e32 v137, v137
	v_rcp_f32_e32 v139, v139
	v_rcp_f32_e32 v3, v3
	v_rcp_f32_e32 v149, v149
	v_mul_f32_e32 v176, v118, v176
	v_mul_f32_e32 v136, v123, v136
	v_mul_f32_e32 v138, v119, v138
	v_mul_f32_e32 v177, v120, v177
	v_mul_f32_e32 v137, v125, v137
	v_mul_f32_e32 v139, v121, v139
	v_mul_f32_e32 v3, v122, v3
	v_mul_f32_e32 v149, v124, v149
	v_cvt_pk_bf16_f32 v136, v3, v136
	v_cvt_pk_bf16_f32 v137, v149, v137
	v_cvt_pk_bf16_f32 v138, v176, v138
	v_cvt_pk_bf16_f32 v139, v177, v139
	s_nop 0
	v_lshlrev_b64 v[152:153], 11, v[174:175]
	global_store_dwordx4 v[140:141], v[136:139], off
	v_lshl_add_u64 v[152:153], v[152:153], 0, v[4:5]
	v_lshlrev_b64 v[152:153], 1, v[152:153]
	v_lshl_add_u64 v[180:181], s[12:13], 0, v[152:153]
	s_nop 0
	v_and_b32_e32 v136, 0xffff0000, v192
	v_lshlrev_b32_e32 v137, 16, v193
	v_and_b32_e32 v138, 0xffff0000, v193
	v_lshlrev_b32_e32 v139, 16, v194
	v_lshlrev_b32_e32 v3, 16, v192
	v_and_b32_e32 v140, 0xffff0000, v194
	v_lshlrev_b32_e32 v141, 16, v195
	v_and_b32_e32 v149, 0xffff0000, v195
	v_mul_f32_e32 v139, 0xbfb8aa3b, v139
	v_mul_f32_e32 v136, 0xbfb8aa3b, v136
	v_mul_f32_e32 v137, 0xbfb8aa3b, v137
	v_mul_f32_e32 v138, 0xbfb8aa3b, v138
	v_mul_f32_e32 v3, 0xbfb8aa3b, v3
	v_mul_f32_e32 v140, 0xbfb8aa3b, v140
	v_mul_f32_e32 v141, 0xbfb8aa3b, v141
	v_mul_f32_e32 v149, 0xbfb8aa3b, v149
	v_exp_f32_e32 v139, v139
	v_exp_f32_e32 v136, v136
	v_exp_f32_e32 v137, v137
	v_exp_f32_e32 v138, v138
	v_exp_f32_e32 v3, v3
	v_exp_f32_e32 v140, v140
	v_exp_f32_e32 v141, v141
	v_exp_f32_e32 v149, v149
	v_add_f32_e32 v139, 1.0, v139
	v_add_f32_e32 v136, 1.0, v136
	v_add_f32_e32 v137, 1.0, v137
	v_add_f32_e32 v138, 1.0, v138
	v_add_f32_e32 v3, 1.0, v3
	v_add_f32_e32 v140, 1.0, v140
	v_add_f32_e32 v141, 1.0, v141
	v_add_f32_e32 v149, 1.0, v149
	v_rcp_f32_e32 v139, v139
	v_rcp_f32_e32 v136, v136
	v_rcp_f32_e32 v137, v137
	v_rcp_f32_e32 v138, v138
	v_rcp_f32_e32 v3, v3
	v_rcp_f32_e32 v140, v140
	v_rcp_f32_e32 v141, v141
	v_rcp_f32_e32 v149, v149
	v_mul_f32_e32 v139, v86, v139
	v_mul_f32_e32 v136, v91, v136
	v_mul_f32_e32 v137, v92, v137
	v_mul_f32_e32 v138, v93, v138
	v_mul_f32_e32 v3, v90, v3
	v_mul_f32_e32 v140, v87, v140
	v_mul_f32_e32 v141, v88, v141
	v_mul_f32_e32 v149, v89, v149
	v_cvt_pk_bf16_f32 v136, v3, v136
	v_cvt_pk_bf16_f32 v137, v137, v138
	v_cvt_pk_bf16_f32 v138, v139, v140
	v_cvt_pk_bf16_f32 v139, v141, v149
	global_store_dwordx4 v[144:145], v[136:139], off
	s_nop 0
	v_lshl_add_u64 v[140:141], s[8:9], 0, v[152:153]
	v_or_b32_e32 v152, 0x100, v152
	v_lshl_add_u64 v[144:145], s[12:13], 0, v[152:153]
	v_lshl_add_u64 v[152:153], s[8:9], 0, v[152:153]
	s_nop 0
	v_lshlrev_b32_e32 v3, 16, v196
	v_and_b32_e32 v136, 0xffff0000, v196
	v_lshlrev_b32_e32 v149, 16, v197
	v_and_b32_e32 v137, 0xffff0000, v197
	v_lshlrev_b32_e32 v176, 16, v198
	v_and_b32_e32 v138, 0xffff0000, v198
	v_lshlrev_b32_e32 v177, 16, v199
	v_and_b32_e32 v139, 0xffff0000, v199
	v_mul_f32_e32 v176, 0xbfb8aa3b, v176
	v_mul_f32_e32 v136, 0xbfb8aa3b, v136
	v_mul_f32_e32 v138, 0xbfb8aa3b, v138
	v_mul_f32_e32 v177, 0xbfb8aa3b, v177
	v_mul_f32_e32 v137, 0xbfb8aa3b, v137
	v_mul_f32_e32 v139, 0xbfb8aa3b, v139
	v_mul_f32_e32 v3, 0xbfb8aa3b, v3
	v_mul_f32_e32 v149, 0xbfb8aa3b, v149
	v_exp_f32_e32 v176, v176
	v_exp_f32_e32 v136, v136
	v_exp_f32_e32 v138, v138
	v_exp_f32_e32 v177, v177
	v_exp_f32_e32 v137, v137
	v_exp_f32_e32 v139, v139
	v_exp_f32_e32 v3, v3
	v_exp_f32_e32 v149, v149
	v_add_f32_e32 v176, 1.0, v176
	v_add_f32_e32 v136, 1.0, v136
	v_add_f32_e32 v138, 1.0, v138
	v_add_f32_e32 v177, 1.0, v177
	v_add_f32_e32 v137, 1.0, v137
	v_add_f32_e32 v139, 1.0, v139
	v_add_f32_e32 v3, 1.0, v3
	v_add_f32_e32 v149, 1.0, v149
	v_rcp_f32_e32 v176, v176
	v_rcp_f32_e32 v136, v136
	v_rcp_f32_e32 v138, v138
	v_rcp_f32_e32 v177, v177
	v_rcp_f32_e32 v137, v137
	v_rcp_f32_e32 v139, v139
	v_rcp_f32_e32 v3, v3
	v_rcp_f32_e32 v149, v149
	v_mul_f32_e32 v176, v110, v176
	v_mul_f32_e32 v136, v115, v136
; __device__ __forceinline__ void unpack8(const u32x4 r, float (&o)[8]) { o[0] = bflo(r.x); o[1] = bfhi(r.x); o[2] = bflo(r.y); o[3] = bfhi(r.y); o[4] = bflo(r.z); o[5] = bfhi(r.z); o[6] = bflo(r.w); o[7] = bfhi(r.w); }
; __device__ __forceinline__ u32x4 pack8(const float (&o)[8]) { u32x4 r; r.x = pk2(o[0], o[1]); r.y = pk2(o[2], o[3]); r.z = pk2(o[4], o[5]); r.w = pk2(o[6], o[7]); return r; }
; __device__ __forceinline__ float sigmoidf_(float x) { return __builtin_amdgcn_rcpf(1.0f + __expf(-x)); }
;     __device__ __forceinline__ bool operator()(f32x4 (&acc)[2][2][4][2], const Unit& u, int wr, int wc, int fr, int fq) const {
;     ...
;                 for (int bj = 0; bj < 2; ++bj) { const size_t off = (size_t)(row0 + ai * 128 + m * 16) * DM + u.pn * 256 + cl0 + bj * 128;
;                     float b[8], r[8]; unpack8(*(const u32x4*)(gp + off), b);
; #pragma unroll
;                     for (int e = 0; e < 4; ++e) { r[e] = acc[ai][bj][m][0][e] * sigmoidf_(b[e]); r[4 + e] = acc[ai][bj][m][1][e] * sigmoidf_(b[4 + e]); }
;                     *(u32x4*)(o + off) = pack8(r); }
	v_mul_f32_e32 v138, v111, v138
	v_mul_f32_e32 v177, v112, v177
	v_mul_f32_e32 v137, v117, v137
	v_mul_f32_e32 v139, v113, v139
	v_mul_f32_e32 v3, v114, v3
	v_mul_f32_e32 v149, v116, v149
	v_cvt_pk_bf16_f32 v136, v3, v136
	v_cvt_pk_bf16_f32 v137, v149, v137
	v_cvt_pk_bf16_f32 v138, v176, v138
	v_cvt_pk_bf16_f32 v139, v177, v139
	s_nop 0
	v_lshlrev_b64 v[144:145], 11, v[172:173]
	global_store_dwordx4 v[140:141], v[136:139], off
	v_lshl_add_u64 v[144:145], v[144:145], 0, v[4:5]
	v_lshlrev_b64 v[144:145], 1, v[144:145]
	v_lshl_add_u64 v[180:181], s[12:13], 0, v[144:145]
	s_nop 0
	v_and_b32_e32 v136, 0xffff0000, v200
	v_lshlrev_b32_e32 v137, 16, v201
	v_and_b32_e32 v138, 0xffff0000, v201
	v_lshlrev_b32_e32 v139, 16, v202
	v_lshlrev_b32_e32 v3, 16, v200
	v_and_b32_e32 v140, 0xffff0000, v202
	v_lshlrev_b32_e32 v141, 16, v203
	v_and_b32_e32 v149, 0xffff0000, v203
	v_mul_f32_e32 v139, 0xbfb8aa3b, v139
	v_mul_f32_e32 v136, 0xbfb8aa3b, v136
	v_mul_f32_e32 v137, 0xbfb8aa3b, v137
	v_mul_f32_e32 v138, 0xbfb8aa3b, v138
	v_mul_f32_e32 v3, 0xbfb8aa3b, v3
	v_mul_f32_e32 v140, 0xbfb8aa3b, v140
	v_mul_f32_e32 v141, 0xbfb8aa3b, v141
	v_mul_f32_e32 v149, 0xbfb8aa3b, v149
	v_exp_f32_e32 v139, v139
	v_exp_f32_e32 v136, v136
	v_exp_f32_e32 v137, v137
	v_exp_f32_e32 v138, v138
	v_exp_f32_e32 v3, v3
	v_exp_f32_e32 v140, v140
	v_exp_f32_e32 v141, v141
	v_exp_f32_e32 v149, v149
	v_add_f32_e32 v139, 1.0, v139
	v_add_f32_e32 v136, 1.0, v136
	v_add_f32_e32 v137, 1.0, v137
	v_add_f32_e32 v138, 1.0, v138
	v_add_f32_e32 v3, 1.0, v3
	v_add_f32_e32 v140, 1.0, v140
	v_add_f32_e32 v141, 1.0, v141
	v_add_f32_e32 v149, 1.0, v149
	v_rcp_f32_e32 v139, v139
	v_rcp_f32_e32 v136, v136
	v_rcp_f32_e32 v137, v137
	v_rcp_f32_e32 v138, v138
	v_rcp_f32_e32 v3, v3
	v_rcp_f32_e32 v140, v140
	v_rcp_f32_e32 v141, v141
	v_rcp_f32_e32 v149, v149
	v_mul_f32_e32 v139, v78, v139
	v_mul_f32_e32 v136, v83, v136
	v_mul_f32_e32 v137, v84, v137
	v_mul_f32_e32 v138, v85, v138
	v_mul_f32_e32 v3, v82, v3
	v_mul_f32_e32 v140, v79, v140
	v_mul_f32_e32 v141, v80, v141
	v_mul_f32_e32 v149, v81, v149
	v_cvt_pk_bf16_f32 v136, v3, v136
	v_cvt_pk_bf16_f32 v137, v137, v138
	v_cvt_pk_bf16_f32 v138, v139, v140
	v_cvt_pk_bf16_f32 v139, v141, v149
	global_store_dwordx4 v[152:153], v[136:139], off
	s_nop 0
	v_lshl_add_u64 v[140:141], s[8:9], 0, v[144:145]
	v_or_b32_e32 v144, 0x100, v144
	v_lshl_add_u64 v[152:153], s[12:13], 0, v[144:145]
	v_lshl_add_u64 v[144:145], s[8:9], 0, v[144:145]
	s_nop 0
	v_lshlrev_b32_e32 v3, 16, v204
	v_and_b32_e32 v136, 0xffff0000, v204
	v_lshlrev_b32_e32 v149, 16, v205
	v_and_b32_e32 v137, 0xffff0000, v205
	v_lshlrev_b32_e32 v176, 16, v206
	v_and_b32_e32 v138, 0xffff0000, v206
	v_lshlrev_b32_e32 v177, 16, v207
	v_and_b32_e32 v139, 0xffff0000, v207
	v_mul_f32_e32 v176, 0xbfb8aa3b, v176
	v_mul_f32_e32 v136, 0xbfb8aa3b, v136
	v_mul_f32_e32 v138, 0xbfb8aa3b, v138
	v_mul_f32_e32 v177, 0xbfb8aa3b, v177
	v_mul_f32_e32 v137, 0xbfb8aa3b, v137
	v_mul_f32_e32 v139, 0xbfb8aa3b, v139
	v_mul_f32_e32 v3, 0xbfb8aa3b, v3
	v_mul_f32_e32 v149, 0xbfb8aa3b, v149
	v_exp_f32_e32 v176, v176
	v_exp_f32_e32 v136, v136
	v_exp_f32_e32 v138, v138
	v_exp_f32_e32 v177, v177
	v_exp_f32_e32 v137, v137
	v_exp_f32_e32 v139, v139
	v_exp_f32_e32 v3, v3
	v_exp_f32_e32 v149, v149
	v_add_f32_e32 v176, 1.0, v176
	v_add_f32_e32 v136, 1.0, v136
	v_add_f32_e32 v138, 1.0, v138
	v_add_f32_e32 v177, 1.0, v177
	v_add_f32_e32 v137, 1.0, v137
	v_add_f32_e32 v139, 1.0, v139
	v_add_f32_e32 v3, 1.0, v3
	v_add_f32_e32 v149, 1.0, v149
	v_rcp_f32_e32 v176, v176
	v_rcp_f32_e32 v136, v136
	v_rcp_f32_e32 v138, v138
	v_rcp_f32_e32 v177, v177
	v_rcp_f32_e32 v137, v137
	v_rcp_f32_e32 v139, v139
	v_rcp_f32_e32 v3, v3
	v_rcp_f32_e32 v149, v149
	v_mul_f32_e32 v176, v102, v176
	v_mul_f32_e32 v136, v107, v136
	v_mul_f32_e32 v138, v103, v138
	v_mul_f32_e32 v177, v104, v177
	v_mul_f32_e32 v137, v109, v137
	v_mul_f32_e32 v139, v105, v139
	v_mul_f32_e32 v3, v106, v3
	v_mul_f32_e32 v149, v108, v149
	v_cvt_pk_bf16_f32 v136, v3, v136
	v_cvt_pk_bf16_f32 v137, v149, v137
	v_cvt_pk_bf16_f32 v138, v176, v138
	v_cvt_pk_bf16_f32 v139, v177, v139
	s_nop 0
	v_lshl_add_u64 v[152:153], v[142:143], 0, s[4:5]
	global_store_dwordx4 v[140:141], v[136:139], off
	v_lshl_add_u64 v[180:181], s[12:13], 0, v[152:153]
	v_lshl_add_u64 v[152:153], s[8:9], 0, v[152:153]
	s_nop 0
	v_and_b32_e32 v136, 0xffff0000, v208
	v_lshlrev_b32_e32 v137, 16, v209
	v_and_b32_e32 v138, 0xffff0000, v209
	v_lshlrev_b32_e32 v139, 16, v210
	v_lshlrev_b32_e32 v3, 16, v208
	v_and_b32_e32 v140, 0xffff0000, v210
	v_lshlrev_b32_e32 v141, 16, v211
	v_and_b32_e32 v149, 0xffff0000, v211
	v_mul_f32_e32 v139, 0xbfb8aa3b, v139
	v_mul_f32_e32 v136, 0xbfb8aa3b, v136
	v_mul_f32_e32 v137, 0xbfb8aa3b, v137
	v_mul_f32_e32 v138, 0xbfb8aa3b, v138
	v_mul_f32_e32 v3, 0xbfb8aa3b, v3
	v_mul_f32_e32 v140, 0xbfb8aa3b, v140
	v_mul_f32_e32 v141, 0xbfb8aa3b, v141
	v_mul_f32_e32 v149, 0xbfb8aa3b, v149
	v_exp_f32_e32 v139, v139
	v_exp_f32_e32 v136, v136
	v_exp_f32_e32 v137, v137
	v_exp_f32_e32 v138, v138
	v_exp_f32_e32 v3, v3
	v_exp_f32_e32 v140, v140
	v_exp_f32_e32 v141, v141
	v_exp_f32_e32 v149, v149
	v_add_f32_e32 v139, 1.0, v139
	v_add_f32_e32 v136, 1.0, v136
	v_add_f32_e32 v137, 1.0, v137
	v_add_f32_e32 v138, 1.0, v138
	v_add_f32_e32 v3, 1.0, v3
	v_add_f32_e32 v140, 1.0, v140
	v_add_f32_e32 v141, 1.0, v141
	v_add_f32_e32 v149, 1.0, v149
	v_rcp_f32_e32 v139, v139
	v_rcp_f32_e32 v136, v136
	v_rcp_f32_e32 v137, v137
	v_rcp_f32_e32 v138, v138
	v_rcp_f32_e32 v3, v3
	v_rcp_f32_e32 v140, v140
	v_rcp_f32_e32 v141, v141
	v_rcp_f32_e32 v149, v149
	v_mul_f32_e32 v139, v70, v139
	v_mul_f32_e32 v136, v75, v136
	v_mul_f32_e32 v137, v76, v137
; __device__ __forceinline__ void unpack8(const u32x4 r, float (&o)[8]) { o[0] = bflo(r.x); o[1] = bfhi(r.x); o[2] = bflo(r.y); o[3] = bfhi(r.y); o[4] = bflo(r.z); o[5] = bfhi(r.z); o[6] = bflo(r.w); o[7] = bfhi(r.w); }
; __device__ __forceinline__ u32x4 pack8(const float (&o)[8]) { u32x4 r; r.x = pk2(o[0], o[1]); r.y = pk2(o[2], o[3]); r.z = pk2(o[4], o[5]); r.w = pk2(o[6], o[7]); return r; }
; __device__ __forceinline__ float sigmoidf_(float x) { return __builtin_amdgcn_rcpf(1.0f + __expf(-x)); }
;     __device__ __forceinline__ bool operator()(f32x4 (&acc)[2][2][4][2], const Unit& u, int wr, int wc, int fr, int fq) const {
;     ...
;                 for (int bj = 0; bj < 2; ++bj) { const size_t off = (size_t)(row0 + ai * 128 + m * 16) * DM + u.pn * 256 + cl0 + bj * 128;
;                     float b[8], r[8]; unpack8(*(const u32x4*)(gp + off), b);
; #pragma unroll
;                     for (int e = 0; e < 4; ++e) { r[e] = acc[ai][bj][m][0][e] * sigmoidf_(b[e]); r[4 + e] = acc[ai][bj][m][1][e] * sigmoidf_(b[4 + e]); }
;                     *(u32x4*)(o + off) = pack8(r); }
	v_mul_f32_e32 v138, v77, v138
	v_mul_f32_e32 v3, v74, v3
	v_mul_f32_e32 v140, v71, v140
	v_mul_f32_e32 v141, v72, v141
	v_mul_f32_e32 v149, v73, v149
	v_cvt_pk_bf16_f32 v136, v3, v136
	v_cvt_pk_bf16_f32 v137, v137, v138
	v_cvt_pk_bf16_f32 v138, v139, v140
	v_cvt_pk_bf16_f32 v139, v141, v149
	global_store_dwordx4 v[144:145], v[136:139], off
	s_nop 0
	v_lshl_add_u64 v[140:141], v[142:143], 0, s[18:19]
	v_lshl_add_u64 v[144:145], s[12:13], 0, v[140:141]
	v_lshl_add_u64 v[140:141], s[8:9], 0, v[140:141]
	s_nop 0
	v_lshlrev_b32_e32 v3, 16, v212
	v_and_b32_e32 v136, 0xffff0000, v212
	v_lshlrev_b32_e32 v149, 16, v213
	v_and_b32_e32 v137, 0xffff0000, v213
	v_lshlrev_b32_e32 v176, 16, v214
	v_and_b32_e32 v138, 0xffff0000, v214
	v_lshlrev_b32_e32 v177, 16, v215
	v_and_b32_e32 v139, 0xffff0000, v215
	v_mul_f32_e32 v176, 0xbfb8aa3b, v176
	v_mul_f32_e32 v136, 0xbfb8aa3b, v136
	v_mul_f32_e32 v138, 0xbfb8aa3b, v138
	v_mul_f32_e32 v177, 0xbfb8aa3b, v177
	v_mul_f32_e32 v137, 0xbfb8aa3b, v137
	v_mul_f32_e32 v139, 0xbfb8aa3b, v139
	v_mul_f32_e32 v3, 0xbfb8aa3b, v3
	v_mul_f32_e32 v149, 0xbfb8aa3b, v149
	v_exp_f32_e32 v176, v176
	v_exp_f32_e32 v136, v136
	v_exp_f32_e32 v138, v138
	v_exp_f32_e32 v177, v177
	v_exp_f32_e32 v137, v137
	v_exp_f32_e32 v139, v139
	v_exp_f32_e32 v3, v3
	v_exp_f32_e32 v149, v149
	v_add_f32_e32 v176, 1.0, v176
	v_add_f32_e32 v136, 1.0, v136
	v_add_f32_e32 v138, 1.0, v138
	v_add_f32_e32 v177, 1.0, v177
	v_add_f32_e32 v137, 1.0, v137
	v_add_f32_e32 v139, 1.0, v139
	v_add_f32_e32 v3, 1.0, v3
	v_add_f32_e32 v149, 1.0, v149
	v_rcp_f32_e32 v176, v176
	v_rcp_f32_e32 v136, v136
	v_rcp_f32_e32 v138, v138
	v_rcp_f32_e32 v177, v177
	v_rcp_f32_e32 v137, v137
	v_rcp_f32_e32 v139, v139
	v_rcp_f32_e32 v3, v3
	v_rcp_f32_e32 v149, v149
	v_mul_f32_e32 v176, v62, v176
	v_mul_f32_e32 v136, v67, v136
	v_mul_f32_e32 v138, v63, v138
	v_mul_f32_e32 v177, v64, v177
	v_mul_f32_e32 v137, v69, v137
	v_mul_f32_e32 v139, v65, v139
	v_mul_f32_e32 v3, v66, v3
	v_mul_f32_e32 v149, v68, v149
	v_cvt_pk_bf16_f32 v136, v3, v136
	v_cvt_pk_bf16_f32 v137, v149, v137
	v_cvt_pk_bf16_f32 v138, v176, v138
	v_cvt_pk_bf16_f32 v139, v177, v139
	s_nop 0
	v_lshl_add_u64 v[144:145], v[142:143], 0, s[20:21]
	global_store_dwordx4 v[152:153], v[136:139], off
	v_lshl_add_u64 v[180:181], s[12:13], 0, v[144:145]
	v_lshl_add_u64 v[144:145], s[8:9], 0, v[144:145]
	s_nop 0
	v_and_b32_e32 v136, 0xffff0000, v216
	v_lshlrev_b32_e32 v137, 16, v217
	v_and_b32_e32 v138, 0xffff0000, v217
	v_lshlrev_b32_e32 v139, 16, v218
	v_lshlrev_b32_e32 v3, 16, v216
	v_and_b32_e32 v149, 0xffff0000, v218
	v_lshlrev_b32_e32 v152, 16, v219
	v_and_b32_e32 v153, 0xffff0000, v219
	v_mul_f32_e32 v139, 0xbfb8aa3b, v139
	v_mul_f32_e32 v136, 0xbfb8aa3b, v136
	v_mul_f32_e32 v137, 0xbfb8aa3b, v137
	v_mul_f32_e32 v138, 0xbfb8aa3b, v138
	v_mul_f32_e32 v3, 0xbfb8aa3b, v3
	v_mul_f32_e32 v149, 0xbfb8aa3b, v149
	v_mul_f32_e32 v152, 0xbfb8aa3b, v152
	v_mul_f32_e32 v153, 0xbfb8aa3b, v153
	v_exp_f32_e32 v139, v139
	v_exp_f32_e32 v136, v136
	v_exp_f32_e32 v137, v137
	v_exp_f32_e32 v138, v138
	v_exp_f32_e32 v3, v3
	v_exp_f32_e32 v149, v149
	v_exp_f32_e32 v152, v152
	v_exp_f32_e32 v153, v153
	v_add_f32_e32 v139, 1.0, v139
	v_add_f32_e32 v136, 1.0, v136
	v_add_f32_e32 v137, 1.0, v137
	v_add_f32_e32 v138, 1.0, v138
	v_add_f32_e32 v3, 1.0, v3
	v_add_f32_e32 v149, 1.0, v149
	v_add_f32_e32 v152, 1.0, v152
	v_add_f32_e32 v153, 1.0, v153
	v_rcp_f32_e32 v139, v139
	v_rcp_f32_e32 v136, v136
	v_rcp_f32_e32 v137, v137
	v_rcp_f32_e32 v138, v138
	v_rcp_f32_e32 v3, v3
	v_rcp_f32_e32 v149, v149
	v_rcp_f32_e32 v152, v152
	v_rcp_f32_e32 v153, v153
	v_mul_f32_e32 v139, v30, v139
	v_mul_f32_e32 v136, v35, v136
	v_mul_f32_e32 v137, v36, v137
	v_mul_f32_e32 v138, v37, v138
	v_mul_f32_e32 v3, v34, v3
	v_mul_f32_e32 v149, v31, v149
	v_mul_f32_e32 v152, v32, v152
	v_mul_f32_e32 v153, v33, v153
	v_cvt_pk_bf16_f32 v136, v3, v136
	v_cvt_pk_bf16_f32 v137, v137, v138
	v_cvt_pk_bf16_f32 v138, v139, v149
	v_cvt_pk_bf16_f32 v139, v152, v153
	global_store_dwordx4 v[140:141], v[136:139], off
	s_nop 0
	v_lshl_add_u64 v[140:141], v[142:143], 0, s[22:23]
	v_lshl_add_u64 v[152:153], s[12:13], 0, v[140:141]
	v_lshl_add_u64 v[140:141], s[8:9], 0, v[140:141]
	s_nop 0
	v_lshlrev_b32_e32 v3, 16, v220
	v_and_b32_e32 v136, 0xffff0000, v220
	v_lshlrev_b32_e32 v149, 16, v221
	v_and_b32_e32 v137, 0xffff0000, v221
	v_lshlrev_b32_e32 v176, 16, v222
	v_and_b32_e32 v138, 0xffff0000, v222
	v_lshlrev_b32_e32 v177, 16, v223
	v_and_b32_e32 v139, 0xffff0000, v223
	v_mul_f32_e32 v176, 0xbfb8aa3b, v176
	v_mul_f32_e32 v136, 0xbfb8aa3b, v136
	v_mul_f32_e32 v138, 0xbfb8aa3b, v138
	v_mul_f32_e32 v177, 0xbfb8aa3b, v177
	v_mul_f32_e32 v137, 0xbfb8aa3b, v137
	v_mul_f32_e32 v139, 0xbfb8aa3b, v139
	v_mul_f32_e32 v3, 0xbfb8aa3b, v3
	v_mul_f32_e32 v149, 0xbfb8aa3b, v149
	v_exp_f32_e32 v176, v176
	v_exp_f32_e32 v136, v136
	v_exp_f32_e32 v138, v138
	v_exp_f32_e32 v177, v177
	v_exp_f32_e32 v137, v137
	v_exp_f32_e32 v139, v139
	v_exp_f32_e32 v3, v3
	v_exp_f32_e32 v149, v149
	v_add_f32_e32 v176, 1.0, v176
	v_add_f32_e32 v136, 1.0, v136
	v_add_f32_e32 v138, 1.0, v138
	v_add_f32_e32 v177, 1.0, v177
	v_add_f32_e32 v137, 1.0, v137
	v_add_f32_e32 v139, 1.0, v139
	v_add_f32_e32 v3, 1.0, v3
	v_add_f32_e32 v149, 1.0, v149
	v_rcp_f32_e32 v176, v176
	v_rcp_f32_e32 v136, v136
	v_rcp_f32_e32 v138, v138
	v_rcp_f32_e32 v177, v177
	v_rcp_f32_e32 v137, v137
	v_rcp_f32_e32 v139, v139
	v_rcp_f32_e32 v3, v3
	v_rcp_f32_e32 v149, v149
	v_mul_f32_e32 v176, v54, v176
	v_mul_f32_e32 v136, v59, v136
	v_mul_f32_e32 v138, v55, v138
	v_mul_f32_e32 v177, v56, v177
	v_mul_f32_e32 v137, v61, v137
	v_mul_f32_e32 v139, v57, v139
; __device__ __forceinline__ void unpack8(const u32x4 r, float (&o)[8]) { o[0] = bflo(r.x); o[1] = bfhi(r.x); o[2] = bflo(r.y); o[3] = bfhi(r.y); o[4] = bflo(r.z); o[5] = bfhi(r.z); o[6] = bflo(r.w); o[7] = bfhi(r.w); }
; __device__ __forceinline__ u32x4 pack8(const float (&o)[8]) { u32x4 r; r.x = pk2(o[0], o[1]); r.y = pk2(o[2], o[3]); r.z = pk2(o[4], o[5]); r.w = pk2(o[6], o[7]); return r; }
; __device__ __forceinline__ float sigmoidf_(float x) { return __builtin_amdgcn_rcpf(1.0f + __expf(-x)); }
;     __device__ __forceinline__ bool operator()(f32x4 (&acc)[2][2][4][2], const Unit& u, int wr, int wc, int fr, int fq) const {
;     ...
;                 for (int bj = 0; bj < 2; ++bj) { const size_t off = (size_t)(row0 + ai * 128 + m * 16) * DM + u.pn * 256 + cl0 + bj * 128;
;                     float b[8], r[8]; unpack8(*(const u32x4*)(gp + off), b);
; #pragma unroll
;                     for (int e = 0; e < 4; ++e) { r[e] = acc[ai][bj][m][0][e] * sigmoidf_(b[e]); r[4 + e] = acc[ai][bj][m][1][e] * sigmoidf_(b[4 + e]); }
;                     *(u32x4*)(o + off) = pack8(r); }
	v_mul_f32_e32 v3, v58, v3
	v_mul_f32_e32 v149, v60, v149
	v_cvt_pk_bf16_f32 v136, v3, v136
	v_cvt_pk_bf16_f32 v137, v149, v137
	v_cvt_pk_bf16_f32 v138, v176, v138
	v_cvt_pk_bf16_f32 v139, v177, v139
	s_nop 0
	v_lshl_add_u64 v[152:153], v[142:143], 0, s[24:25]
	global_store_dwordx4 v[144:145], v[136:139], off
	v_lshl_add_u64 v[180:181], s[12:13], 0, v[152:153]
	v_lshl_add_u64 v[152:153], s[8:9], 0, v[152:153]
	s_nop 0
	v_and_b32_e32 v136, 0xffff0000, v226
	v_lshlrev_b32_e32 v137, 16, v227
	v_and_b32_e32 v138, 0xffff0000, v227
	v_lshlrev_b32_e32 v139, 16, v228
	v_lshlrev_b32_e32 v3, 16, v226
	v_and_b32_e32 v144, 0xffff0000, v228
	v_lshlrev_b32_e32 v145, 16, v229
	v_and_b32_e32 v149, 0xffff0000, v229
	v_mul_f32_e32 v139, 0xbfb8aa3b, v139
	v_mul_f32_e32 v136, 0xbfb8aa3b, v136
	v_mul_f32_e32 v137, 0xbfb8aa3b, v137
	v_mul_f32_e32 v138, 0xbfb8aa3b, v138
	v_mul_f32_e32 v3, 0xbfb8aa3b, v3
	v_mul_f32_e32 v144, 0xbfb8aa3b, v144
	v_mul_f32_e32 v145, 0xbfb8aa3b, v145
	v_mul_f32_e32 v149, 0xbfb8aa3b, v149
	v_exp_f32_e32 v139, v139
	v_exp_f32_e32 v136, v136
	v_exp_f32_e32 v137, v137
	v_exp_f32_e32 v138, v138
	v_exp_f32_e32 v3, v3
	v_exp_f32_e32 v144, v144
	v_exp_f32_e32 v145, v145
	v_exp_f32_e32 v149, v149
	v_add_f32_e32 v139, 1.0, v139
	v_add_f32_e32 v136, 1.0, v136
	v_add_f32_e32 v137, 1.0, v137
	v_add_f32_e32 v138, 1.0, v138
	v_add_f32_e32 v3, 1.0, v3
	v_add_f32_e32 v144, 1.0, v144
	v_add_f32_e32 v145, 1.0, v145
	v_add_f32_e32 v149, 1.0, v149
	v_rcp_f32_e32 v139, v139
	v_rcp_f32_e32 v136, v136
	v_rcp_f32_e32 v137, v137
	v_rcp_f32_e32 v138, v138
	v_rcp_f32_e32 v3, v3
	v_rcp_f32_e32 v144, v144
	v_rcp_f32_e32 v145, v145
	v_rcp_f32_e32 v149, v149
	v_mul_f32_e32 v139, v22, v139
	v_mul_f32_e32 v136, v27, v136
	v_mul_f32_e32 v137, v28, v137
	v_mul_f32_e32 v138, v29, v138
	v_mul_f32_e32 v3, v26, v3
	v_mul_f32_e32 v144, v23, v144
	v_mul_f32_e32 v145, v24, v145
	v_mul_f32_e32 v149, v25, v149
	v_cvt_pk_bf16_f32 v136, v3, v136
	v_cvt_pk_bf16_f32 v137, v137, v138
	v_cvt_pk_bf16_f32 v138, v139, v144
	v_cvt_pk_bf16_f32 v139, v145, v149
	global_store_dwordx4 v[140:141], v[136:139], off
	s_nop 0
	v_lshl_add_u64 v[140:141], v[142:143], 0, s[26:27]
	v_lshl_add_u64 v[144:145], s[12:13], 0, v[140:141]
	v_lshl_add_u64 v[140:141], s[8:9], 0, v[140:141]
	s_nop 0
	v_lshlrev_b32_e32 v3, 16, v230
	v_and_b32_e32 v136, 0xffff0000, v230
	v_lshlrev_b32_e32 v149, 16, v231
	v_and_b32_e32 v137, 0xffff0000, v231
	v_lshlrev_b32_e32 v176, 16, v232
	v_and_b32_e32 v138, 0xffff0000, v232
	v_lshlrev_b32_e32 v177, 16, v233
	v_and_b32_e32 v139, 0xffff0000, v233
	v_mul_f32_e32 v176, 0xbfb8aa3b, v176
	v_mul_f32_e32 v136, 0xbfb8aa3b, v136
	v_mul_f32_e32 v138, 0xbfb8aa3b, v138
	v_mul_f32_e32 v177, 0xbfb8aa3b, v177
	v_mul_f32_e32 v137, 0xbfb8aa3b, v137
	v_mul_f32_e32 v139, 0xbfb8aa3b, v139
	v_mul_f32_e32 v3, 0xbfb8aa3b, v3
	v_mul_f32_e32 v149, 0xbfb8aa3b, v149
	v_exp_f32_e32 v176, v176
	v_exp_f32_e32 v136, v136
	v_exp_f32_e32 v138, v138
	v_exp_f32_e32 v177, v177
	v_exp_f32_e32 v137, v137
	v_exp_f32_e32 v139, v139
	v_exp_f32_e32 v3, v3
	v_exp_f32_e32 v149, v149
	v_add_f32_e32 v176, 1.0, v176
	v_add_f32_e32 v136, 1.0, v136
	v_add_f32_e32 v138, 1.0, v138
	v_add_f32_e32 v177, 1.0, v177
	v_add_f32_e32 v137, 1.0, v137
	v_add_f32_e32 v139, 1.0, v139
	v_add_f32_e32 v3, 1.0, v3
	v_add_f32_e32 v149, 1.0, v149
	v_rcp_f32_e32 v176, v176
	v_rcp_f32_e32 v136, v136
	v_rcp_f32_e32 v138, v138
	v_rcp_f32_e32 v177, v177
	v_rcp_f32_e32 v137, v137
	v_rcp_f32_e32 v139, v139
	v_rcp_f32_e32 v3, v3
	v_rcp_f32_e32 v149, v149
	v_mul_f32_e32 v176, v46, v176
	v_mul_f32_e32 v136, v51, v136
	v_mul_f32_e32 v138, v47, v138
	v_mul_f32_e32 v177, v48, v177
	v_mul_f32_e32 v137, v53, v137
	v_mul_f32_e32 v139, v49, v139
	v_mul_f32_e32 v3, v50, v3
	v_mul_f32_e32 v149, v52, v149
	v_cvt_pk_bf16_f32 v136, v3, v136
	v_cvt_pk_bf16_f32 v137, v149, v137
	v_cvt_pk_bf16_f32 v138, v176, v138
	v_cvt_pk_bf16_f32 v139, v177, v139
	s_nop 0
	v_lshl_add_u64 v[144:145], v[142:143], 0, s[28:29]
	global_store_dwordx4 v[152:153], v[136:139], off
	v_lshl_add_u64 v[180:181], s[12:13], 0, v[144:145]
	v_lshl_add_u64 v[144:145], s[8:9], 0, v[144:145]
	s_nop 0
	v_and_b32_e32 v136, 0xffff0000, v236
	v_lshlrev_b32_e32 v137, 16, v237
	v_and_b32_e32 v138, 0xffff0000, v237
	v_lshlrev_b32_e32 v139, 16, v238
	v_lshlrev_b32_e32 v3, 16, v236
	v_and_b32_e32 v149, 0xffff0000, v238
	v_lshlrev_b32_e32 v152, 16, v239
	v_and_b32_e32 v153, 0xffff0000, v239
	v_mul_f32_e32 v139, 0xbfb8aa3b, v139
	v_mul_f32_e32 v136, 0xbfb8aa3b, v136
	v_mul_f32_e32 v137, 0xbfb8aa3b, v137
	v_mul_f32_e32 v138, 0xbfb8aa3b, v138
	v_mul_f32_e32 v3, 0xbfb8aa3b, v3
	v_mul_f32_e32 v149, 0xbfb8aa3b, v149
	v_mul_f32_e32 v152, 0xbfb8aa3b, v152
; __device__ __forceinline__ void unpack8(const u32x4 r, float (&o)[8]) { o[0] = bflo(r.x); o[1] = bfhi(r.x); o[2] = bflo(r.y); o[3] = bfhi(r.y); o[4] = bflo(r.z); o[5] = bfhi(r.z); o[6] = bflo(r.w); o[7] = bfhi(r.w); }
; __device__ __forceinline__ u32x4 pack8(const float (&o)[8]) { u32x4 r; r.x = pk2(o[0], o[1]); r.y = pk2(o[2], o[3]); r.z = pk2(o[4], o[5]); r.w = pk2(o[6], o[7]); return r; }
; __device__ __forceinline__ float sigmoidf_(float x) { return __builtin_amdgcn_rcpf(1.0f + __expf(-x)); }
;     __device__ __forceinline__ bool operator()(f32x4 (&acc)[2][2][4][2], const Unit& u, int wr, int wc, int fr, int fq) const {
;     ...
;                 for (int bj = 0; bj < 2; ++bj) { const size_t off = (size_t)(row0 + ai * 128 + m * 16) * DM + u.pn * 256 + cl0 + bj * 128;
;                     float b[8], r[8]; unpack8(*(const u32x4*)(gp + off), b);
; #pragma unroll
;                     for (int e = 0; e < 4; ++e) { r[e] = acc[ai][bj][m][0][e] * sigmoidf_(b[e]); r[4 + e] = acc[ai][bj][m][1][e] * sigmoidf_(b[4 + e]); }
;                     *(u32x4*)(o + off) = pack8(r); }
	v_mul_f32_e32 v153, 0xbfb8aa3b, v153
	v_exp_f32_e32 v139, v139
	v_exp_f32_e32 v136, v136
	v_exp_f32_e32 v137, v137
	v_exp_f32_e32 v138, v138
	v_exp_f32_e32 v3, v3
	v_exp_f32_e32 v149, v149
	v_exp_f32_e32 v152, v152
	v_exp_f32_e32 v153, v153
	v_add_f32_e32 v139, 1.0, v139
	v_add_f32_e32 v136, 1.0, v136
	v_add_f32_e32 v137, 1.0, v137
	v_add_f32_e32 v138, 1.0, v138
	v_add_f32_e32 v3, 1.0, v3
	v_add_f32_e32 v149, 1.0, v149
	v_add_f32_e32 v152, 1.0, v152
	v_add_f32_e32 v153, 1.0, v153
	v_rcp_f32_e32 v139, v139
	v_rcp_f32_e32 v136, v136
	v_rcp_f32_e32 v137, v137
	v_rcp_f32_e32 v138, v138
	v_rcp_f32_e32 v3, v3
	v_rcp_f32_e32 v149, v149
	v_rcp_f32_e32 v152, v152
	v_rcp_f32_e32 v153, v153
	v_mul_f32_e32 v139, v14, v139
	v_mul_f32_e32 v136, v19, v136
	v_mul_f32_e32 v137, v20, v137
	v_mul_f32_e32 v138, v21, v138
	v_mul_f32_e32 v3, v18, v3
	v_mul_f32_e32 v149, v15, v149
	v_mul_f32_e32 v152, v16, v152
	v_mul_f32_e32 v153, v17, v153
	v_cvt_pk_bf16_f32 v136, v3, v136
	v_cvt_pk_bf16_f32 v137, v137, v138
	v_cvt_pk_bf16_f32 v138, v139, v149
	v_cvt_pk_bf16_f32 v139, v152, v153
	global_store_dwordx4 v[140:141], v[136:139], off
	s_nop 0
	v_lshl_add_u64 v[140:141], v[142:143], 0, s[30:31]
	v_lshl_add_u64 v[152:153], s[12:13], 0, v[140:141]
	v_lshl_add_u64 v[140:141], s[8:9], 0, v[140:141]
	s_nop 0
	v_lshlrev_b32_e32 v3, 16, v240
	v_and_b32_e32 v136, 0xffff0000, v240
	v_lshlrev_b32_e32 v149, 16, v241
	v_and_b32_e32 v137, 0xffff0000, v241
	v_lshlrev_b32_e32 v176, 16, v242
	v_and_b32_e32 v138, 0xffff0000, v242
	v_lshlrev_b32_e32 v177, 16, v243
	v_and_b32_e32 v139, 0xffff0000, v243
	v_mul_f32_e32 v176, 0xbfb8aa3b, v176
	v_mul_f32_e32 v136, 0xbfb8aa3b, v136
	v_mul_f32_e32 v138, 0xbfb8aa3b, v138
	v_mul_f32_e32 v177, 0xbfb8aa3b, v177
	v_mul_f32_e32 v137, 0xbfb8aa3b, v137
	v_mul_f32_e32 v139, 0xbfb8aa3b, v139
	v_mul_f32_e32 v3, 0xbfb8aa3b, v3
	v_mul_f32_e32 v149, 0xbfb8aa3b, v149
	v_exp_f32_e32 v176, v176
	v_exp_f32_e32 v136, v136
	v_exp_f32_e32 v138, v138
	v_exp_f32_e32 v177, v177
	v_exp_f32_e32 v137, v137
	v_exp_f32_e32 v139, v139
	v_exp_f32_e32 v3, v3
	v_exp_f32_e32 v149, v149
	v_add_f32_e32 v176, 1.0, v176
	v_add_f32_e32 v136, 1.0, v136
	v_add_f32_e32 v138, 1.0, v138
	v_add_f32_e32 v177, 1.0, v177
	v_add_f32_e32 v137, 1.0, v137
	v_add_f32_e32 v139, 1.0, v139
	v_add_f32_e32 v3, 1.0, v3
	v_add_f32_e32 v149, 1.0, v149
	v_rcp_f32_e32 v176, v176
	v_rcp_f32_e32 v136, v136
	v_rcp_f32_e32 v138, v138
	v_rcp_f32_e32 v177, v177
	v_rcp_f32_e32 v137, v137
	v_rcp_f32_e32 v139, v139
	v_rcp_f32_e32 v3, v3
	v_rcp_f32_e32 v149, v149
	v_mul_f32_e32 v176, v38, v176
	v_mul_f32_e32 v136, v43, v136
	v_mul_f32_e32 v138, v39, v138
	v_mul_f32_e32 v177, v40, v177
	v_mul_f32_e32 v137, v45, v137
	v_mul_f32_e32 v139, v41, v139
	v_mul_f32_e32 v3, v42, v3
	v_mul_f32_e32 v149, v44, v149
	v_cvt_pk_bf16_f32 v136, v3, v136
	v_cvt_pk_bf16_f32 v137, v149, v137
	v_cvt_pk_bf16_f32 v138, v176, v138
	v_cvt_pk_bf16_f32 v139, v177, v139
	s_nop 0
	s_nop 0
	v_lshlrev_b32_e32 v3, 16, v244
	global_store_dwordx4 v[144:145], v[136:139], off
	v_and_b32_e32 v144, 0xffff0000, v246
	v_lshlrev_b32_e32 v145, 16, v247
	v_and_b32_e32 v136, 0xffff0000, v244
	v_lshlrev_b32_e32 v137, 16, v245
	v_and_b32_e32 v138, 0xffff0000, v245
	v_lshlrev_b32_e32 v139, 16, v246
	v_and_b32_e32 v149, 0xffff0000, v247
	v_mul_f32_e32 v139, 0xbfb8aa3b, v139
	v_mul_f32_e32 v136, 0xbfb8aa3b, v136
	v_mul_f32_e32 v137, 0xbfb8aa3b, v137
	v_mul_f32_e32 v138, 0xbfb8aa3b, v138
	v_mul_f32_e32 v3, 0xbfb8aa3b, v3
	v_mul_f32_e32 v144, 0xbfb8aa3b, v144
	v_mul_f32_e32 v145, 0xbfb8aa3b, v145
	v_mul_f32_e32 v149, 0xbfb8aa3b, v149
	v_exp_f32_e32 v139, v139
	v_exp_f32_e32 v136, v136
	v_exp_f32_e32 v137, v137
	v_exp_f32_e32 v138, v138
	v_exp_f32_e32 v3, v3
	v_exp_f32_e32 v144, v144
	v_exp_f32_e32 v145, v145
	v_exp_f32_e32 v149, v149
	v_add_f32_e32 v139, 1.0, v139
	v_add_f32_e32 v136, 1.0, v136
	v_add_f32_e32 v137, 1.0, v137
	v_add_f32_e32 v138, 1.0, v138
	v_add_f32_e32 v3, 1.0, v3
	v_add_f32_e32 v144, 1.0, v144
	v_add_f32_e32 v145, 1.0, v145
	v_add_f32_e32 v149, 1.0, v149
	v_rcp_f32_e32 v139, v139
	v_rcp_f32_e32 v136, v136
	v_rcp_f32_e32 v137, v137
	v_rcp_f32_e32 v138, v138
	v_rcp_f32_e32 v3, v3
	v_rcp_f32_e32 v144, v144
	v_rcp_f32_e32 v145, v145
	v_rcp_f32_e32 v149, v149
	v_mul_f32_e32 v139, v6, v139
	v_mul_f32_e32 v136, v11, v136
	v_mul_f32_e32 v137, v12, v137
	v_mul_f32_e32 v138, v13, v138
	v_mul_f32_e32 v3, v10, v3
	v_mul_f32_e32 v144, v7, v144
	v_mul_f32_e32 v145, v8, v145
	v_mul_f32_e32 v149, v9, v149
	v_cvt_pk_bf16_f32 v136, v3, v136
	v_cvt_pk_bf16_f32 v137, v137, v138
	v_cvt_pk_bf16_f32 v138, v139, v144
	v_cvt_pk_bf16_f32 v139, v145, v149
	global_store_dwordx4 v[140:141], v[136:139], off
	s_cbranch_execnz .LBB0_617
